# v1 + SwiGLU epilogue batched 8-wide (ILP), saddr stores
# baseline (speedup 1.0000x reference)
; __device__ __forceinline__ unsigned cvt_pk_bf16(float lo, float hi) { unsigned r; asm volatile("v_cvt_pk_bf16_f32 %0, %1, %2" : "=v"(r) : "v"(lo), "v"(hi)); return r; }
; __device__ __forceinline__ float fsigmoid(float x) { return __builtin_amdgcn_rcpf(1.f + __expf(-x)); }
;     __device__ __forceinline__ void operator()(const f32x4 (&acc)[2][2][4][2], const Unit& u, int wr, int wc, int fr, int fq) const {
;         const int row0 = u.pm * BM + wr * 64 + fr, col0 = u.pn * HALF + wc * 32 + 8 * fq;
; #pragma unroll
;         for (int ai = 0; ai < 2; ++ai)
; #pragma unroll
;             for (int m = 0; m < 4; ++m) { const f32x4 g0 = acc[ai][0][m][0], g1 = acc[ai][0][m][1], u0 = acc[ai][1][m][0], u1 = acc[ai][1][m][1];
;                 u32x4 w;
;                 w.x = cvt_pk_bf16(g0[0] * fsigmoid(g0[0]) * u0[0], g0[1] * fsigmoid(g0[1]) * u0[1]); w.y = cvt_pk_bf16(g0[2] * fsigmoid(g0[2]) * u0[2], g0[3] * fsigmoid(g0[3]) * u0[3]);
;                 w.z = cvt_pk_bf16(g1[0] * fsigmoid(g1[0]) * u1[0], g1[1] * fsigmoid(g1[1]) * u1[1]); w.w = cvt_pk_bf16(g1[2] * fsigmoid(g1[2]) * u1[2], g1[3] * fsigmoid(g1[3]) * u1[3]);
;                 *(u32x4*)(O + (size_t)(row0 + ai * HALF + m * 16) * 2816 + col0) = w; }
.LBB0_778:
	v_lshl_add_u32 v147, s42, 8, v1
	v_lshl_or_b32 v142, s43, 7, v145
	v_readlane_b32 s42, v254, 48
	v_readlane_b32 s43, v254, 49
	v_mul_lo_u32 v147, v147, s93
	v_lshl_add_u32 v147, v142, 1, v147
	v_mul_f32_e32 v202, 0xbfb8aa3b, v126
	v_mul_f32_e32 v203, 0xbfb8aa3b, v127
	v_mul_f32_e32 v204, 0xbfb8aa3b, v128
	v_mul_f32_e32 v205, 0xbfb8aa3b, v129
	v_mul_f32_e32 v206, 0xbfb8aa3b, v118
	v_mul_f32_e32 v207, 0xbfb8aa3b, v119
	v_mul_f32_e32 v208, 0xbfb8aa3b, v120
	v_mul_f32_e32 v209, 0xbfb8aa3b, v121
	v_exp_f32_e32 v202, v202
	v_exp_f32_e32 v203, v203
	v_exp_f32_e32 v204, v204
	v_exp_f32_e32 v205, v205
	v_exp_f32_e32 v206, v206
	v_exp_f32_e32 v207, v207
	v_exp_f32_e32 v208, v208
	v_exp_f32_e32 v209, v209
	v_add_f32_e32 v202, 1.0, v202
	v_add_f32_e32 v203, 1.0, v203
	v_add_f32_e32 v204, 1.0, v204
	v_add_f32_e32 v205, 1.0, v205
	v_add_f32_e32 v206, 1.0, v206
	v_add_f32_e32 v207, 1.0, v207
	v_add_f32_e32 v208, 1.0, v208
	v_add_f32_e32 v209, 1.0, v209
	v_rcp_f32_e32 v202, v202
	v_rcp_f32_e32 v203, v203
	v_rcp_f32_e32 v204, v204
	v_rcp_f32_e32 v205, v205
	v_rcp_f32_e32 v206, v206
	v_rcp_f32_e32 v207, v207
	v_rcp_f32_e32 v208, v208
	v_rcp_f32_e32 v209, v209
	v_mul_f32_e32 v126, v126, v202
	v_mul_f32_e32 v127, v127, v203
	v_mul_f32_e32 v128, v128, v204
	v_mul_f32_e32 v129, v129, v205
	v_mul_f32_e32 v118, v118, v206
	v_mul_f32_e32 v119, v119, v207
	v_mul_f32_e32 v120, v120, v208
	v_mul_f32_e32 v121, v121, v209
	v_mul_f32_e32 v126, v126, v122
	v_mul_f32_e32 v127, v127, v123
	v_mul_f32_e32 v128, v128, v124
	v_mul_f32_e32 v129, v129, v125
	v_mul_f32_e32 v118, v118, v114
	v_mul_f32_e32 v119, v119, v115
	v_mul_f32_e32 v120, v120, v116
	v_mul_f32_e32 v121, v121, v117
	v_cvt_pk_bf16_f32 v122, v126, v127
	v_cvt_pk_bf16_f32 v123, v128, v129
	v_cvt_pk_bf16_f32 v124, v118, v119
	v_cvt_pk_bf16_f32 v125, v120, v121
	global_store_dwordx4 v147, v[122:125], s[42:43]
	v_mul_f32_e32 v202, 0xbfb8aa3b, v110
	v_mul_f32_e32 v203, 0xbfb8aa3b, v111
	v_mul_f32_e32 v204, 0xbfb8aa3b, v112
	v_mul_f32_e32 v205, 0xbfb8aa3b, v113
	v_mul_f32_e32 v206, 0xbfb8aa3b, v102
	v_mul_f32_e32 v207, 0xbfb8aa3b, v103
	v_mul_f32_e32 v208, 0xbfb8aa3b, v104
	v_mul_f32_e32 v209, 0xbfb8aa3b, v105
	v_exp_f32_e32 v202, v202
	v_exp_f32_e32 v203, v203
	v_exp_f32_e32 v204, v204
	v_exp_f32_e32 v205, v205
	v_exp_f32_e32 v206, v206
	v_exp_f32_e32 v207, v207
	v_exp_f32_e32 v208, v208
	v_exp_f32_e32 v209, v209
	v_add_f32_e32 v202, 1.0, v202
	v_add_f32_e32 v203, 1.0, v203
	v_add_f32_e32 v204, 1.0, v204
	v_add_f32_e32 v205, 1.0, v205
	v_add_f32_e32 v206, 1.0, v206
	v_add_f32_e32 v207, 1.0, v207
	v_add_f32_e32 v208, 1.0, v208
	v_add_f32_e32 v209, 1.0, v209
	v_rcp_f32_e32 v202, v202
	v_rcp_f32_e32 v203, v203
	v_rcp_f32_e32 v204, v204
	v_rcp_f32_e32 v205, v205
	v_rcp_f32_e32 v206, v206
	v_rcp_f32_e32 v207, v207
	v_rcp_f32_e32 v208, v208
	v_rcp_f32_e32 v209, v209
	v_mul_f32_e32 v110, v110, v202
	v_mul_f32_e32 v111, v111, v203
	v_mul_f32_e32 v112, v112, v204
	v_mul_f32_e32 v113, v113, v205
	v_mul_f32_e32 v102, v102, v206
	v_mul_f32_e32 v103, v103, v207
	v_mul_f32_e32 v104, v104, v208
	v_mul_f32_e32 v105, v105, v209
	v_mul_f32_e32 v110, v110, v106
	v_mul_f32_e32 v111, v111, v107
	v_mul_f32_e32 v112, v112, v108
	v_mul_f32_e32 v113, v113, v109
	v_mul_f32_e32 v102, v102, v98
	v_mul_f32_e32 v103, v103, v99
	v_mul_f32_e32 v104, v104, v100
	v_mul_f32_e32 v105, v105, v101
	v_cvt_pk_bf16_f32 v106, v110, v111
	v_cvt_pk_bf16_f32 v107, v112, v113
	v_cvt_pk_bf16_f32 v108, v102, v103
	v_cvt_pk_bf16_f32 v109, v104, v105
	v_add_u32_e32 v210, 0x16000, v147
	global_store_dwordx4 v210, v[106:109], s[42:43]
	v_mul_f32_e32 v202, 0xbfb8aa3b, v94
	v_mul_f32_e32 v203, 0xbfb8aa3b, v95
	v_mul_f32_e32 v204, 0xbfb8aa3b, v96
	v_mul_f32_e32 v205, 0xbfb8aa3b, v97
	v_mul_f32_e32 v206, 0xbfb8aa3b, v86
	v_mul_f32_e32 v207, 0xbfb8aa3b, v87
	v_mul_f32_e32 v208, 0xbfb8aa3b, v88
	v_mul_f32_e32 v209, 0xbfb8aa3b, v89
	v_exp_f32_e32 v202, v202
	v_exp_f32_e32 v203, v203
	v_exp_f32_e32 v204, v204
	v_exp_f32_e32 v205, v205
	v_exp_f32_e32 v206, v206
	v_exp_f32_e32 v207, v207
	v_exp_f32_e32 v208, v208
	v_exp_f32_e32 v209, v209
	v_add_f32_e32 v202, 1.0, v202
	v_add_f32_e32 v203, 1.0, v203
	v_add_f32_e32 v204, 1.0, v204
	v_add_f32_e32 v205, 1.0, v205
	v_add_f32_e32 v206, 1.0, v206
	v_add_f32_e32 v207, 1.0, v207
	v_add_f32_e32 v208, 1.0, v208
	v_add_f32_e32 v209, 1.0, v209
	v_rcp_f32_e32 v202, v202
	v_rcp_f32_e32 v203, v203
	v_rcp_f32_e32 v204, v204
	v_rcp_f32_e32 v205, v205
	v_rcp_f32_e32 v206, v206
	v_rcp_f32_e32 v207, v207
	v_rcp_f32_e32 v208, v208
	v_rcp_f32_e32 v209, v209
	v_mul_f32_e32 v94, v94, v202
	v_mul_f32_e32 v95, v95, v203
	v_mul_f32_e32 v96, v96, v204
	v_mul_f32_e32 v97, v97, v205
	v_mul_f32_e32 v86, v86, v206
	v_mul_f32_e32 v87, v87, v207
	v_mul_f32_e32 v88, v88, v208
	v_mul_f32_e32 v89, v89, v209
	v_mul_f32_e32 v94, v94, v90
	v_mul_f32_e32 v95, v95, v91
	v_mul_f32_e32 v96, v96, v92
	v_mul_f32_e32 v97, v97, v93
	v_mul_f32_e32 v86, v86, v82
	v_mul_f32_e32 v87, v87, v83
	v_mul_f32_e32 v88, v88, v84
	v_mul_f32_e32 v89, v89, v85
	v_cvt_pk_bf16_f32 v90, v94, v95
	v_cvt_pk_bf16_f32 v91, v96, v97
	v_cvt_pk_bf16_f32 v92, v86, v87
	v_cvt_pk_bf16_f32 v93, v88, v89
	v_add_u32_e32 v210, 0x2c000, v147
	global_store_dwordx4 v210, v[90:93], s[42:43]
	v_mul_f32_e32 v202, 0xbfb8aa3b, v78
	v_mul_f32_e32 v203, 0xbfb8aa3b, v79
	v_mul_f32_e32 v204, 0xbfb8aa3b, v80
	v_mul_f32_e32 v205, 0xbfb8aa3b, v81
	v_mul_f32_e32 v206, 0xbfb8aa3b, v70
	v_mul_f32_e32 v207, 0xbfb8aa3b, v71
	v_mul_f32_e32 v208, 0xbfb8aa3b, v72
	v_mul_f32_e32 v209, 0xbfb8aa3b, v73
	v_exp_f32_e32 v202, v202
	v_exp_f32_e32 v203, v203
	v_exp_f32_e32 v204, v204
	v_exp_f32_e32 v205, v205
; __device__ __forceinline__ unsigned cvt_pk_bf16(float lo, float hi) { unsigned r; asm volatile("v_cvt_pk_bf16_f32 %0, %1, %2" : "=v"(r) : "v"(lo), "v"(hi)); return r; }
; __device__ __forceinline__ float fsigmoid(float x) { return __builtin_amdgcn_rcpf(1.f + __expf(-x)); }
;     __device__ __forceinline__ void operator()(const f32x4 (&acc)[2][2][4][2], const Unit& u, int wr, int wc, int fr, int fq) const {
;     ...
;             for (int m = 0; m < 4; ++m) { const f32x4 g0 = acc[ai][0][m][0], g1 = acc[ai][0][m][1], u0 = acc[ai][1][m][0], u1 = acc[ai][1][m][1];
;                 u32x4 w;
;                 w.x = cvt_pk_bf16(g0[0] * fsigmoid(g0[0]) * u0[0], g0[1] * fsigmoid(g0[1]) * u0[1]); w.y = cvt_pk_bf16(g0[2] * fsigmoid(g0[2]) * u0[2], g0[3] * fsigmoid(g0[3]) * u0[3]);
;                 w.z = cvt_pk_bf16(g1[0] * fsigmoid(g1[0]) * u1[0], g1[1] * fsigmoid(g1[1]) * u1[1]); w.w = cvt_pk_bf16(g1[2] * fsigmoid(g1[2]) * u1[2], g1[3] * fsigmoid(g1[3]) * u1[3]);
;                 *(u32x4*)(O + (size_t)(row0 + ai * HALF + m * 16) * 2816 + col0) = w; }
	v_exp_f32_e32 v206, v206
	v_exp_f32_e32 v207, v207
	v_exp_f32_e32 v208, v208
	v_exp_f32_e32 v209, v209
	v_add_f32_e32 v202, 1.0, v202
	v_add_f32_e32 v203, 1.0, v203
	v_add_f32_e32 v204, 1.0, v204
	v_add_f32_e32 v205, 1.0, v205
	v_add_f32_e32 v206, 1.0, v206
	v_add_f32_e32 v207, 1.0, v207
	v_add_f32_e32 v208, 1.0, v208
	v_add_f32_e32 v209, 1.0, v209
	v_rcp_f32_e32 v202, v202
	v_rcp_f32_e32 v203, v203
	v_rcp_f32_e32 v204, v204
	v_rcp_f32_e32 v205, v205
	v_rcp_f32_e32 v206, v206
	v_rcp_f32_e32 v207, v207
	v_rcp_f32_e32 v208, v208
	v_rcp_f32_e32 v209, v209
	v_mul_f32_e32 v78, v78, v202
	v_mul_f32_e32 v79, v79, v203
	v_mul_f32_e32 v80, v80, v204
	v_mul_f32_e32 v81, v81, v205
	v_mul_f32_e32 v70, v70, v206
	v_mul_f32_e32 v71, v71, v207
	v_mul_f32_e32 v72, v72, v208
	v_mul_f32_e32 v73, v73, v209
	v_mul_f32_e32 v78, v78, v74
	v_mul_f32_e32 v79, v79, v75
	v_mul_f32_e32 v80, v80, v76
	v_mul_f32_e32 v81, v81, v77
	v_mul_f32_e32 v70, v70, v66
	v_mul_f32_e32 v71, v71, v67
	v_mul_f32_e32 v72, v72, v68
	v_mul_f32_e32 v73, v73, v69
	v_cvt_pk_bf16_f32 v74, v78, v79
	v_cvt_pk_bf16_f32 v75, v80, v81
	v_cvt_pk_bf16_f32 v76, v70, v71
	v_cvt_pk_bf16_f32 v77, v72, v73
	v_add_u32_e32 v210, 0x42000, v147
	global_store_dwordx4 v210, v[74:77], s[42:43]
	v_mul_f32_e32 v202, 0xbfb8aa3b, v62
	v_mul_f32_e32 v203, 0xbfb8aa3b, v63
	v_mul_f32_e32 v204, 0xbfb8aa3b, v64
	v_mul_f32_e32 v205, 0xbfb8aa3b, v65
	v_mul_f32_e32 v206, 0xbfb8aa3b, v54
	v_mul_f32_e32 v207, 0xbfb8aa3b, v55
	v_mul_f32_e32 v208, 0xbfb8aa3b, v56
	v_mul_f32_e32 v209, 0xbfb8aa3b, v57
	v_exp_f32_e32 v202, v202
	v_exp_f32_e32 v203, v203
	v_exp_f32_e32 v204, v204
	v_exp_f32_e32 v205, v205
	v_exp_f32_e32 v206, v206
	v_exp_f32_e32 v207, v207
	v_exp_f32_e32 v208, v208
	v_exp_f32_e32 v209, v209
	v_add_f32_e32 v202, 1.0, v202
	v_add_f32_e32 v203, 1.0, v203
	v_add_f32_e32 v204, 1.0, v204
	v_add_f32_e32 v205, 1.0, v205
	v_add_f32_e32 v206, 1.0, v206
	v_add_f32_e32 v207, 1.0, v207
	v_add_f32_e32 v208, 1.0, v208
	v_add_f32_e32 v209, 1.0, v209
	v_rcp_f32_e32 v202, v202
	v_rcp_f32_e32 v203, v203
	v_rcp_f32_e32 v204, v204
	v_rcp_f32_e32 v205, v205
	v_rcp_f32_e32 v206, v206
	v_rcp_f32_e32 v207, v207
	v_rcp_f32_e32 v208, v208
	v_rcp_f32_e32 v209, v209
	v_mul_f32_e32 v62, v62, v202
	v_mul_f32_e32 v63, v63, v203
	v_mul_f32_e32 v64, v64, v204
	v_mul_f32_e32 v65, v65, v205
	v_mul_f32_e32 v54, v54, v206
	v_mul_f32_e32 v55, v55, v207
	v_mul_f32_e32 v56, v56, v208
	v_mul_f32_e32 v57, v57, v209
	v_mul_f32_e32 v62, v62, v58
	v_mul_f32_e32 v63, v63, v59
	v_mul_f32_e32 v64, v64, v60
	v_mul_f32_e32 v65, v65, v61
	v_mul_f32_e32 v54, v54, v50
	v_mul_f32_e32 v55, v55, v51
	v_mul_f32_e32 v56, v56, v52
	v_mul_f32_e32 v57, v57, v53
	v_cvt_pk_bf16_f32 v58, v62, v63
	v_cvt_pk_bf16_f32 v59, v64, v65
	v_cvt_pk_bf16_f32 v60, v54, v55
	v_cvt_pk_bf16_f32 v61, v56, v57
	v_add_u32_e32 v210, 0xb0000, v147
	global_store_dwordx4 v210, v[58:61], s[42:43]
	v_mul_f32_e32 v202, 0xbfb8aa3b, v46
	v_mul_f32_e32 v203, 0xbfb8aa3b, v47
	v_mul_f32_e32 v204, 0xbfb8aa3b, v48
	v_mul_f32_e32 v205, 0xbfb8aa3b, v49
	v_mul_f32_e32 v206, 0xbfb8aa3b, v38
	v_mul_f32_e32 v207, 0xbfb8aa3b, v39
	v_mul_f32_e32 v208, 0xbfb8aa3b, v40
	v_mul_f32_e32 v209, 0xbfb8aa3b, v41
	v_exp_f32_e32 v202, v202
	v_exp_f32_e32 v203, v203
	v_exp_f32_e32 v204, v204
	v_exp_f32_e32 v205, v205
	v_exp_f32_e32 v206, v206
	v_exp_f32_e32 v207, v207
	v_exp_f32_e32 v208, v208
	v_exp_f32_e32 v209, v209
	v_add_f32_e32 v202, 1.0, v202
	v_add_f32_e32 v203, 1.0, v203
	v_add_f32_e32 v204, 1.0, v204
	v_add_f32_e32 v205, 1.0, v205
	v_add_f32_e32 v206, 1.0, v206
	v_add_f32_e32 v207, 1.0, v207
	v_add_f32_e32 v208, 1.0, v208
	v_add_f32_e32 v209, 1.0, v209
	v_rcp_f32_e32 v202, v202
	v_rcp_f32_e32 v203, v203
	v_rcp_f32_e32 v204, v204
	v_rcp_f32_e32 v205, v205
	v_rcp_f32_e32 v206, v206
	v_rcp_f32_e32 v207, v207
	v_rcp_f32_e32 v208, v208
	v_rcp_f32_e32 v209, v209
	v_mul_f32_e32 v46, v46, v202
	v_mul_f32_e32 v47, v47, v203
	v_mul_f32_e32 v48, v48, v204
	v_mul_f32_e32 v49, v49, v205
; __device__ __forceinline__ unsigned cvt_pk_bf16(float lo, float hi) { unsigned r; asm volatile("v_cvt_pk_bf16_f32 %0, %1, %2" : "=v"(r) : "v"(lo), "v"(hi)); return r; }
; __device__ __forceinline__ float fsigmoid(float x) { return __builtin_amdgcn_rcpf(1.f + __expf(-x)); }
;     __device__ __forceinline__ void operator()(const f32x4 (&acc)[2][2][4][2], const Unit& u, int wr, int wc, int fr, int fq) const {
;     ...
;             for (int m = 0; m < 4; ++m) { const f32x4 g0 = acc[ai][0][m][0], g1 = acc[ai][0][m][1], u0 = acc[ai][1][m][0], u1 = acc[ai][1][m][1];
;                 u32x4 w;
;                 w.x = cvt_pk_bf16(g0[0] * fsigmoid(g0[0]) * u0[0], g0[1] * fsigmoid(g0[1]) * u0[1]); w.y = cvt_pk_bf16(g0[2] * fsigmoid(g0[2]) * u0[2], g0[3] * fsigmoid(g0[3]) * u0[3]);
;                 w.z = cvt_pk_bf16(g1[0] * fsigmoid(g1[0]) * u1[0], g1[1] * fsigmoid(g1[1]) * u1[1]); w.w = cvt_pk_bf16(g1[2] * fsigmoid(g1[2]) * u1[2], g1[3] * fsigmoid(g1[3]) * u1[3]);
;                 *(u32x4*)(O + (size_t)(row0 + ai * HALF + m * 16) * 2816 + col0) = w; }
	v_mul_f32_e32 v38, v38, v206
	v_mul_f32_e32 v39, v39, v207
	v_mul_f32_e32 v40, v40, v208
	v_mul_f32_e32 v41, v41, v209
	v_mul_f32_e32 v46, v46, v42
	v_mul_f32_e32 v47, v47, v43
	v_mul_f32_e32 v48, v48, v44
	v_mul_f32_e32 v49, v49, v45
	v_mul_f32_e32 v38, v38, v34
	v_mul_f32_e32 v39, v39, v35
	v_mul_f32_e32 v40, v40, v36
	v_mul_f32_e32 v41, v41, v37
	v_cvt_pk_bf16_f32 v42, v46, v47
	v_cvt_pk_bf16_f32 v43, v48, v49
	v_cvt_pk_bf16_f32 v44, v38, v39
	v_cvt_pk_bf16_f32 v45, v40, v41
	v_add_u32_e32 v210, 0xc6000, v147
	global_store_dwordx4 v210, v[42:45], s[42:43]
	v_mul_f32_e32 v202, 0xbfb8aa3b, v30
	v_mul_f32_e32 v203, 0xbfb8aa3b, v31
	v_mul_f32_e32 v204, 0xbfb8aa3b, v32
	v_mul_f32_e32 v205, 0xbfb8aa3b, v33
	v_mul_f32_e32 v206, 0xbfb8aa3b, v22
	v_mul_f32_e32 v207, 0xbfb8aa3b, v23
	v_mul_f32_e32 v208, 0xbfb8aa3b, v24
	v_mul_f32_e32 v209, 0xbfb8aa3b, v25
	v_exp_f32_e32 v202, v202
	v_exp_f32_e32 v203, v203
	v_exp_f32_e32 v204, v204
	v_exp_f32_e32 v205, v205
	v_exp_f32_e32 v206, v206
	v_exp_f32_e32 v207, v207
	v_exp_f32_e32 v208, v208
	v_exp_f32_e32 v209, v209
	v_add_f32_e32 v202, 1.0, v202
	v_add_f32_e32 v203, 1.0, v203
	v_add_f32_e32 v204, 1.0, v204
	v_add_f32_e32 v205, 1.0, v205
	v_add_f32_e32 v206, 1.0, v206
	v_add_f32_e32 v207, 1.0, v207
	v_add_f32_e32 v208, 1.0, v208
	v_add_f32_e32 v209, 1.0, v209
	v_rcp_f32_e32 v202, v202
	v_rcp_f32_e32 v203, v203
	v_rcp_f32_e32 v204, v204
	v_rcp_f32_e32 v205, v205
	v_rcp_f32_e32 v206, v206
	v_rcp_f32_e32 v207, v207
	v_rcp_f32_e32 v208, v208
	v_rcp_f32_e32 v209, v209
	v_mul_f32_e32 v30, v30, v202
	v_mul_f32_e32 v31, v31, v203
	v_mul_f32_e32 v32, v32, v204
	v_mul_f32_e32 v33, v33, v205
	v_mul_f32_e32 v22, v22, v206
	v_mul_f32_e32 v23, v23, v207
	v_mul_f32_e32 v24, v24, v208
	v_mul_f32_e32 v25, v25, v209
	v_mul_f32_e32 v30, v30, v26
	v_mul_f32_e32 v31, v31, v27
	v_mul_f32_e32 v32, v32, v28
	v_mul_f32_e32 v33, v33, v29
	v_mul_f32_e32 v22, v22, v18
	v_mul_f32_e32 v23, v23, v19
	v_mul_f32_e32 v24, v24, v20
	v_mul_f32_e32 v25, v25, v21
	v_cvt_pk_bf16_f32 v26, v30, v31
	v_cvt_pk_bf16_f32 v27, v32, v33
	v_cvt_pk_bf16_f32 v28, v22, v23
	v_cvt_pk_bf16_f32 v29, v24, v25
	v_add_u32_e32 v210, 0xdc000, v147
	global_store_dwordx4 v210, v[26:29], s[42:43]
	v_mul_f32_e32 v202, 0xbfb8aa3b, v14
	v_mul_f32_e32 v203, 0xbfb8aa3b, v15
	v_mul_f32_e32 v204, 0xbfb8aa3b, v16
	v_mul_f32_e32 v205, 0xbfb8aa3b, v17
	v_mul_f32_e32 v206, 0xbfb8aa3b, v6
	v_mul_f32_e32 v207, 0xbfb8aa3b, v7
	v_mul_f32_e32 v208, 0xbfb8aa3b, v8
	v_mul_f32_e32 v209, 0xbfb8aa3b, v9
	v_exp_f32_e32 v202, v202
	v_exp_f32_e32 v203, v203
	v_exp_f32_e32 v204, v204
	v_exp_f32_e32 v205, v205
	v_exp_f32_e32 v206, v206
	v_exp_f32_e32 v207, v207
	v_exp_f32_e32 v208, v208
	v_exp_f32_e32 v209, v209
	v_add_f32_e32 v202, 1.0, v202
	v_add_f32_e32 v203, 1.0, v203
	v_add_f32_e32 v204, 1.0, v204
	v_add_f32_e32 v205, 1.0, v205
	v_add_f32_e32 v206, 1.0, v206
	v_add_f32_e32 v207, 1.0, v207
	v_add_f32_e32 v208, 1.0, v208
	v_add_f32_e32 v209, 1.0, v209
	v_rcp_f32_e32 v202, v202
	v_rcp_f32_e32 v203, v203
	v_rcp_f32_e32 v204, v204
	v_rcp_f32_e32 v205, v205
	v_rcp_f32_e32 v206, v206
	v_rcp_f32_e32 v207, v207
	v_rcp_f32_e32 v208, v208
	v_rcp_f32_e32 v209, v209
	v_mul_f32_e32 v14, v14, v202
	v_mul_f32_e32 v15, v15, v203
	v_mul_f32_e32 v16, v16, v204
	v_mul_f32_e32 v17, v17, v205
	v_mul_f32_e32 v6, v6, v206
	v_mul_f32_e32 v7, v7, v207
	v_mul_f32_e32 v8, v8, v208
	v_mul_f32_e32 v9, v9, v209
	v_mul_f32_e32 v14, v14, v10
	v_mul_f32_e32 v15, v15, v11
	v_mul_f32_e32 v16, v16, v12
	v_mul_f32_e32 v17, v17, v13
	v_mul_f32_e32 v6, v6, v2
	v_mul_f32_e32 v7, v7, v3
	v_mul_f32_e32 v8, v8, v4
	v_mul_f32_e32 v9, v9, v5
	v_cvt_pk_bf16_f32 v10, v14, v15
	v_cvt_pk_bf16_f32 v11, v16, v17
	v_cvt_pk_bf16_f32 v12, v6, v7
	v_cvt_pk_bf16_f32 v13, v8, v9
	v_add_u32_e32 v210, 0xf2000, v147
	global_store_dwordx4 v210, v[10:13], s[42:43]
	s_andn2_b64 vcc, exec, s[38:39]
	s_mov_b64 s[42:43], -1
	s_cbranch_vccnz .LBB0_771
	s_andn2_b64 vcc, exec, s[0:1]
	s_cbranch_vccnz .LBB0_770
	s_barrier
	s_branch .LBB0_770
